# MoBA home combine: partial loads of the three ranks issued together, single wait (was three serial L2 round trips)
# baseline (speedup 1.0000x reference)
.LBB0_1962:
	s_waitcnt vmcnt(0)
	s_waitcnt lgkmcnt(0)
	s_barrier
	s_waitcnt vmcnt(7)
	v_mov_b32_e32 v2, v170
	v_mov_b32_e32 v3, v14
	s_waitcnt vmcnt(0)
	buffer_inv sc1
	v_permlane32_swap_b32_e32 v14, v3
	v_lshl_add_u32 v4, v2, 1, v2
	v_add_f32_e32 v3, v14, v3
	v_cmp_ne_u32_sdwa s[20:21], v179, v167 src0_sel:BYTE_0 src1_sel:DWORD
	v_ashrrev_i32_e32 v5, 31, v4
	v_and_b32_e32 v6, 0xff00, v179
	v_cmp_ne_u32_e64 s[22:23], 0, v6
	v_and_b32_e32 v7, 0xff0000, v179
	v_cmp_ne_u32_e64 s[24:25], 0, v7
	s_mov_b64 s[18:19], exec
	v_lshlrev_b64 v[14:15], 2, v[4:5]
	v_lshlrev_b64 v[6:7], 8, v[4:5]
	v_lshl_add_u64 v[126:127], s[48:49], 0, v[14:15]
	v_lshl_add_u64 v[128:129], s[46:47], 0, v[14:15]
	v_lshl_add_u64 v[4:5], v[172:173], 0, v[6:7]
	s_and_b64 exec, s[18:19], s[20:21]
	global_load_dword v88, v[126:127], off
	global_load_dwordx4 v[6:9], v[4:5], off
	global_load_dwordx4 v[10:13], v[4:5], off offset:128
	global_load_dwordx4 v[64:67], v[4:5], off offset:32
	global_load_dwordx4 v[68:71], v[4:5], off offset:160
	global_load_dwordx4 v[72:75], v[4:5], off offset:64
	global_load_dwordx4 v[76:79], v[4:5], off offset:192
	global_load_dwordx4 v[80:83], v[4:5], off offset:96
	global_load_dwordx4 v[84:87], v[4:5], off offset:224
	global_load_dword v15, v[128:129], off
	s_and_b64 exec, s[18:19], s[22:23]
	global_load_dword v114, v[126:127], off offset:4
	global_load_dwordx4 v[90:93], v[4:5], off offset:256
	global_load_dwordx4 v[94:97], v[4:5], off offset:384
	global_load_dwordx4 v[98:101], v[4:5], off offset:288
	global_load_dwordx4 v[102:105], v[4:5], off offset:416
	global_load_dwordx4 v[106:109], v[4:5], off offset:320
	global_load_dwordx4 v[110:113], v[4:5], off offset:448
	global_load_dwordx4 v[116:119], v[4:5], off offset:352
	global_load_dwordx4 v[120:123], v[4:5], off offset:480
	global_load_dword v125, v[128:129], off offset:4
	s_and_b64 exec, s[18:19], s[24:25]
	global_load_dword v89, v[126:127], off offset:8
	global_load_dwordx4 v[130:133], v[4:5], off offset:512
	global_load_dwordx4 v[134:137], v[4:5], off offset:640
	global_load_dwordx4 v[138:141], v[4:5], off offset:544
	global_load_dwordx4 v[142:145], v[4:5], off offset:672
	global_load_dwordx4 v[146:149], v[4:5], off offset:576
	global_load_dwordx4 v[150:153], v[4:5], off offset:704
	global_load_dwordx4 v[154:157], v[4:5], off offset:608
	global_load_dwordx4 v[158:161], v[4:5], off offset:736
	global_load_dword v163, v[128:129], off offset:8
	s_mov_b64 exec, s[18:19]
	s_waitcnt vmcnt(0)
	s_and_b64 exec, s[18:19], s[20:21]
	v_sub_f32_e32 v14, v88, v1
	v_exp_f32_e32 v14, v14
	s_nop 0
	v_pk_fma_f32 v[48:49], v[6:7], v[14:15], v[48:49] op_sel_hi:[1,0,1]
	v_pk_fma_f32 v[50:51], v[8:9], v[14:15], v[50:51] op_sel_hi:[1,0,1]
	v_pk_fma_f32 v[32:33], v[10:11], v[14:15], v[32:33] op_sel_hi:[1,0,1]
	v_pk_fma_f32 v[34:35], v[12:13], v[14:15], v[34:35] op_sel_hi:[1,0,1]
	v_pk_fma_f32 v[52:53], v[64:65], v[14:15], v[52:53] op_sel_hi:[1,0,1]
	v_pk_fma_f32 v[54:55], v[66:67], v[14:15], v[54:55] op_sel_hi:[1,0,1]
	v_pk_fma_f32 v[36:37], v[68:69], v[14:15], v[36:37] op_sel_hi:[1,0,1]
	v_pk_fma_f32 v[38:39], v[70:71], v[14:15], v[38:39] op_sel_hi:[1,0,1]
	v_pk_fma_f32 v[56:57], v[72:73], v[14:15], v[56:57] op_sel_hi:[1,0,1]
	v_pk_fma_f32 v[58:59], v[74:75], v[14:15], v[58:59] op_sel_hi:[1,0,1]
	v_pk_fma_f32 v[40:41], v[76:77], v[14:15], v[40:41] op_sel_hi:[1,0,1]
	v_pk_fma_f32 v[42:43], v[78:79], v[14:15], v[42:43] op_sel_hi:[1,0,1]
	v_pk_fma_f32 v[60:61], v[80:81], v[14:15], v[60:61] op_sel_hi:[1,0,1]
	v_pk_fma_f32 v[62:63], v[82:83], v[14:15], v[62:63] op_sel_hi:[1,0,1]
	v_pk_fma_f32 v[44:45], v[84:85], v[14:15], v[44:45] op_sel_hi:[1,0,1]
	v_pk_fma_f32 v[46:47], v[86:87], v[14:15], v[46:47] op_sel_hi:[1,0,1]
	v_fmac_f32_e32 v3, v14, v15
	s_and_b64 exec, s[18:19], s[22:23]
	v_sub_f32_e32 v124, v114, v1
	v_exp_f32_e32 v124, v124
	s_nop 0
	v_pk_fma_f32 v[48:49], v[90:91], v[124:125], v[48:49] op_sel_hi:[1,0,1]
	v_pk_fma_f32 v[50:51], v[92:93], v[124:125], v[50:51] op_sel_hi:[1,0,1]
	v_pk_fma_f32 v[32:33], v[94:95], v[124:125], v[32:33] op_sel_hi:[1,0,1]
	v_pk_fma_f32 v[34:35], v[96:97], v[124:125], v[34:35] op_sel_hi:[1,0,1]
	v_pk_fma_f32 v[52:53], v[98:99], v[124:125], v[52:53] op_sel_hi:[1,0,1]
	v_pk_fma_f32 v[54:55], v[100:101], v[124:125], v[54:55] op_sel_hi:[1,0,1]
	v_pk_fma_f32 v[36:37], v[102:103], v[124:125], v[36:37] op_sel_hi:[1,0,1]
	v_pk_fma_f32 v[38:39], v[104:105], v[124:125], v[38:39] op_sel_hi:[1,0,1]
	v_pk_fma_f32 v[56:57], v[106:107], v[124:125], v[56:57] op_sel_hi:[1,0,1]
	v_pk_fma_f32 v[58:59], v[108:109], v[124:125], v[58:59] op_sel_hi:[1,0,1]
	v_pk_fma_f32 v[40:41], v[110:111], v[124:125], v[40:41] op_sel_hi:[1,0,1]
	v_pk_fma_f32 v[42:43], v[112:113], v[124:125], v[42:43] op_sel_hi:[1,0,1]
	v_pk_fma_f32 v[60:61], v[116:117], v[124:125], v[60:61] op_sel_hi:[1,0,1]
	v_pk_fma_f32 v[62:63], v[118:119], v[124:125], v[62:63] op_sel_hi:[1,0,1]
	v_pk_fma_f32 v[44:45], v[120:121], v[124:125], v[44:45] op_sel_hi:[1,0,1]
	v_pk_fma_f32 v[46:47], v[122:123], v[124:125], v[46:47] op_sel_hi:[1,0,1]
	v_fmac_f32_e32 v3, v124, v125
	s_and_b64 exec, s[18:19], s[24:25]
	v_sub_f32_e32 v162, v89, v1
	v_exp_f32_e32 v162, v162
	s_nop 0
	v_pk_fma_f32 v[48:49], v[130:131], v[162:163], v[48:49] op_sel_hi:[1,0,1]
	v_pk_fma_f32 v[50:51], v[132:133], v[162:163], v[50:51] op_sel_hi:[1,0,1]
	v_pk_fma_f32 v[32:33], v[134:135], v[162:163], v[32:33] op_sel_hi:[1,0,1]
	v_pk_fma_f32 v[34:35], v[136:137], v[162:163], v[34:35] op_sel_hi:[1,0,1]
	v_pk_fma_f32 v[52:53], v[138:139], v[162:163], v[52:53] op_sel_hi:[1,0,1]
	v_pk_fma_f32 v[54:55], v[140:141], v[162:163], v[54:55] op_sel_hi:[1,0,1]
	v_pk_fma_f32 v[36:37], v[142:143], v[162:163], v[36:37] op_sel_hi:[1,0,1]
	v_pk_fma_f32 v[38:39], v[144:145], v[162:163], v[38:39] op_sel_hi:[1,0,1]
	v_pk_fma_f32 v[56:57], v[146:147], v[162:163], v[56:57] op_sel_hi:[1,0,1]
	v_pk_fma_f32 v[58:59], v[148:149], v[162:163], v[58:59] op_sel_hi:[1,0,1]
	v_pk_fma_f32 v[40:41], v[150:151], v[162:163], v[40:41] op_sel_hi:[1,0,1]
	v_pk_fma_f32 v[42:43], v[152:153], v[162:163], v[42:43] op_sel_hi:[1,0,1]
	v_pk_fma_f32 v[60:61], v[154:155], v[162:163], v[60:61] op_sel_hi:[1,0,1]
	v_pk_fma_f32 v[62:63], v[156:157], v[162:163], v[62:63] op_sel_hi:[1,0,1]
	v_pk_fma_f32 v[44:45], v[158:159], v[162:163], v[44:45] op_sel_hi:[1,0,1]
	v_pk_fma_f32 v[46:47], v[160:161], v[162:163], v[46:47] op_sel_hi:[1,0,1]
	v_fmac_f32_e32 v3, v162, v163
	s_mov_b64 exec, s[18:19]
	s_branch .LBB0_1872
